# SBA attention phase: one static s_setprio 1 for waves 4-7 on entry (reset on exit), later code placement unchanged
# baseline (speedup 1.0000x reference)
; __device__ __forceinline__ int rho_row(int k) { return (k & 32) | ((k & 4) << 2) | ((k & 24) >> 1) | (k & 3); }
; __device__ __forceinline__ void phase_sba_attn(const Params& p, u16* sm) {
;   const int tid = threadIdx.x, lane = tid & 63, wave = tid >> 6, fr = lane & 15, fq = lane >> 4;
;   u16* sK0 = sm; u16* sV0 = sm + 64 * LDSP;
;   bf16x8 tri[2], ones;
; #pragma unroll
;   for (int bb = 0; bb < 2; ++bb) {
;     uint32_t w[4];
; #pragma unroll
;     for (int i2 = 0; i2 < 4; ++i2) {
;       const int s_ = 8 * (fr >> 2) + 4 * bb + (fr & 3);
;       const int j0 = 8 * fq + 2 * i2, j1 = j0 + 1;
;       w[i2] = (j0 > s_ ? 0x3F80u : 0u) | ((j1 > s_ ? 0x3F80u : 0u) << 16);
;     }
;     tri[bb] = mk_frag(w[0], w[1], w[2], w[3]);
;   }
;   ones = mk_frag(0x3F803F80u, 0x3F803F80u, 0x3F803F80u, 0x3F803F80u);
;   const int ntiles = 128 * 32;
;   for (int tile = blockIdx.x; tile < ntiles; tile += gridDim.x) {
;     const int qt = 31 - (tile >> 7), bh = tile & 127;
;     const int b = bh >> 4, h = bh & 15;
;     const int myq = qt * 128 + wave * 16 + fr;
;     bf16x8 qf[2];
; #pragma unroll
;     for (int ks = 0; ks < 2; ++ks) qf[ks] = *(const bf16x8*)(p.qb + ((size_t)b * SEQ + myq) * DM + h * 64 + ks * 32 + fq * 8);
;     f32x4 o[4];
; #pragma unroll
;     for (int dm = 0; dm < 4; ++dm) o[dm] = (f32x4){0.f, 0.f, 0.f, 0.f};
;     float carry = 0.f;
;     const int pc = tid & 7, pr = tid >> 3, prl = rho_row(pr);
;     const u16* kbase = p.kb + ((size_t)b * SEQ) * DM + h * 64 + (size_t)pr * DM + pc * 8;
;     const u16* vbase = p.vT + ((size_t)(b * 16 + h) * 64 + pr) * SEQ + pc * 8;
;     uint4 rk = *(const uint4*)(kbase + (size_t)(2 * qt + 1) * 64 * DM);
;     uint4 rv = *(const uint4*)(vbase + (2 * qt + 1) * 64);
;     int buf = 0;
.LBB0_320:
	s_add_u32 s56, s72, 0x13808400
	s_addc_u32 s57, s73, 0
	s_cmp_lt_i32 s74, 3
	s_cselect_b64 s[0:1], -1, 0
	s_cmp_gt_i32 s75, 1
	s_cselect_b64 s[4:5], -1, 0
	s_and_b64 s[0:1], s[0:1], s[4:5]
	s_andn2_b64 vcc, exec, s[0:1]
	s_cbranch_vccnz .LBB0_386
	v_readfirstlane_b32 s0, v192
	s_cmp_lt_u32 s0, 0x100
	s_cbranch_scc1 .Lsbaprio_skip
	s_setprio 1
.Lsbaprio_skip:
	s_cmpk_gt_i32 s2, 0xfff
	s_cbranch_scc1 .LBB0_342
	s_load_dword s0, s[96:97], 0xb0
	s_add_u32 s1, s96, 0xb0
	v_mov_b32_e32 v1, 0
	s_addc_u32 s3, s97, 0
	global_load_dword v3, v1, s[96:97] offset:190
	s_waitcnt lgkmcnt(0)
	s_cmp_lt_u32 s2, s0
	s_cselect_b32 s4, 12, 18
	s_add_u32 s4, s1, s4
	s_addc_u32 s5, s3, 0
	global_load_ushort v13, v1, s[4:5]
	v_bfe_u32 v4, v192, 4, 2
	v_lshlrev_b32_e32 v5, 1, v192
	v_and_b32_e32 v6, 3, v192
	v_lshlrev_b32_e32 v60, 3, v4
	v_and_or_b32 v5, v5, 24, v6
	v_lshrrev_b32_e32 v2, 4, v192
	v_mov_b32_e32 v7, 0x3f80
	v_lshlrev_b32_e32 v10, 3, v192
	v_cmp_gt_u32_e32 vcc, v60, v5
	v_and_b32_e32 v6, 12, v2
	v_and_b32_e32 v2, 56, v10
	v_lshlrev_b32_e32 v97, 4, v4
	v_lshlrev_b32_e32 v12, 2, v4
	v_or_b32_e32 v4, 4, v5
	v_cndmask_b32_e32 v10, 0, v7, vcc
	v_cmp_lt_u32_e32 vcc, v60, v5
	v_lshrrev_b32_e32 v9, 1, v192
	v_lshrrev_b32_e32 v8, 2, v192
	v_cndmask_b32_e64 v11, 1.0, 0, vcc
	v_cmp_gt_u32_e32 vcc, v60, v4
	v_lshrrev_b32_e32 v94, 3, v192
	v_bfe_u32 v14, v0, 10, 10
	v_bfe_u32 v15, v0, 20, 10
	v_and_b32_e32 v0, 16, v9
	v_or_b32_e32 v9, 2, v60
	v_cndmask_b32_e32 v18, 0, v7, vcc
	v_cmp_lt_u32_e32 vcc, v60, v4
	v_and_b32_e32 v95, 0xf0, v8
	v_and_b32_e32 v8, 35, v94
	v_cndmask_b32_e64 v19, 1.0, 0, vcc
	v_cmp_gt_u32_e32 vcc, v9, v4
	v_or_b32_e32 v16, 6, v60
	v_or3_b32 v8, v8, v0, v6
	v_lshlrev_b32_e32 v0, 1, v2
	v_cndmask_b32_e32 v20, 0, v7, vcc
	v_cmp_lt_u32_e32 vcc, v9, v4
	v_lshl_add_u64 v[66:67], s[6:7], 0, v[0:1]
	v_or_b32_e32 v6, v10, v11
	v_cndmask_b32_e64 v21, 1.0, 0, vcc
	v_cmp_gt_u32_e32 vcc, v16, v4
	v_or_b32_e32 v17, 4, v60
	v_and_b32_e32 v61, 15, v192
	v_cndmask_b32_e32 v10, 0, v7, vcc
	v_cmp_lt_u32_e32 vcc, v16, v4
	s_mov_b32 s21, 0
	v_lshlrev_b32_e32 v62, 11, v94
	v_cndmask_b32_e64 v11, 1.0, 0, vcc
	v_cmp_gt_u32_e32 vcc, v9, v5
	v_mov_b32_e32 v63, v1
	v_mul_u32_u24_e32 v96, 0x90, v94
	v_cndmask_b32_e32 v22, 0, v7, vcc
	v_cmp_lt_u32_e32 vcc, v9, v5
	v_mul_u32_u24_e32 v98, 0x90, v61
	v_mov_b32_e32 v65, v1
	v_cndmask_b32_e64 v9, 1.0, 0, vcc
	v_cmp_gt_u32_e32 vcc, v17, v5
	v_lshlrev_b32_e32 v64, 1, v60
	v_mul_u32_u24_e32 v99, 0x90, v8
	v_cndmask_b32_e32 v23, 0, v7, vcc
	v_cmp_lt_u32_e32 vcc, v17, v5
	v_or_b32_e32 v4, v18, v19
	v_or_b32_e32 v9, v22, v9
	v_cndmask_b32_e64 v17, 1.0, 0, vcc
	v_cmp_gt_u32_e32 vcc, v16, v5
	v_mov_b32_e32 v8, v6
	v_lshlrev_b32_e32 v68, 1, v2
	v_cndmask_b32_e32 v24, 0, v7, vcc
	v_cmp_lt_u32_e32 vcc, v16, v5
	v_or_b32_e32 v5, v20, v21
	v_or_b32_e32 v7, v10, v11
	v_cndmask_b32_e64 v16, 1.0, 0, vcc
	v_or_b32_e32 v10, v23, v17
	v_or_b32_e32 v11, v24, v16
	v_mov_b32_e32 v69, v1
	s_waitcnt vmcnt(0)
	v_lshrrev_b32_e32 v0, 16, v3
	v_and_b32_e32 v3, 0xffff, v3
	v_mad_u32_u24 v14, v15, v3, v14
	s_mov_b32 s1, 0xc316199a
	s_mov_b32 s22, 0x3e38aa3b
	v_mul_lo_u32 v3, v3, v13
	v_bfe_i32 v3, v3, 0, 24
	v_mul_lo_u32 v0, v3, v0
	v_add_u32_e32 v0, 63, v0
	v_and_b32_e32 v0, 0xffffffc0, v0
	v_cmp_ne_u32_e64 s[6:7], 64, v0
	v_mbcnt_lo_u32_b32 v0, -1, 0
	v_mbcnt_hi_u32_b32 v111, -1, v0
	v_mad_u64_u32 v[14:15], s[4:5], v14, v13, v[192:193]
	v_and_or_b32 v0, v111, 64, v61
	v_lshrrev_b32_e32 v100, 6, v14
	v_cmp_lt_u32_e64 s[4:5], 63, v14
	s_mov_b32 s16, 0x3f803f80
	v_mov_b32_e32 v101, 0x80
	v_mov_b32_e32 v102, 0x100
	v_mov_b32_e32 v103, 0x200
	v_mov_b32_e32 v104, 0x400
	v_mov_b32_e32 v105, 0x800
	v_mov_b32_e32 v106, 0x1000
	v_mov_b32_e32 v107, 0x2000
	v_mov_b32_e32 v108, 0x4000
	v_mov_b32_e32 v109, 0x8000
	v_mov_b32_e32 v110, 0x20000
	v_lshlrev_b32_e32 v70, 1, v12
	v_lshlrev_b32_e32 v112, 2, v0
	s_mov_b32 s3, s2
	s_branch .LBB0_324

; __device__ __forceinline__ void phase_sba_attn(const Params& p, u16* sm) {
;     ...
;       bf16x8 Lh[2], Ll[2];
; #pragma unroll
;       for (int k2 = 0; k2 < 2; ++k2) {
;         uint32_t hw[4], lw[4];
; #pragma unroll
;         for (int e2 = 0; e2 < 4; ++e2) {
;           const int mt = 2 * k2 + (e2 >> 1), j = (e2 & 1) * 2;
;           hw[e2] = pack2(L[mt][j], L[mt][j + 1]);
;           const float r0 = L[mt][j] - __uint_as_float(hw[e2] << 16), r1 = L[mt][j + 1] - __uint_as_float(hw[e2] & 0xffff0000u);
;           lw[e2] = pack2(r0, r1);
;         }
;         Lh[k2] = mk_frag(hw[0], hw[1], hw[2], hw[3]);
;         Ll[k2] = mk_frag(lw[0], lw[1], lw[2], lw[3]);
;       }
;       f32x4 cum[4];
; #pragma unroll
;       for (int ms = 0; ms < 4; ++ms) {
;         const int a = ms >> 1, bb = ms & 1;
;         f32x4 c = (f32x4){0.f, 0.f, 0.f, 0.f};
;         c = mfma16(tri[bb], Lh[a], c);
;         c = mfma16(tri[bb], Ll[a], c);
;         if (a == 0) { c = mfma16(ones, Lh[1], c); c = mfma16(ones, Ll[1], c); }
;         cum[ms] = c;
;       }
;       float tot = cum[0][0] + L[0][0];
;       tot = __shfl(tot, fr);
;       bf16x8 pf[2];
; #pragma unroll
;       for (int k2 = 0; k2 < 2; ++k2) {
;         uint32_t pw[4];
; #pragma unroll
;         for (int e2 = 0; e2 < 4; ++e2) {
;           const int mt = 2 * k2 + (e2 >> 1), j = (e2 & 1) * 2;
;           float p0 = __builtin_amdgcn_exp2f(lb[mt][j] + cum[mt][j] + carry);
;           float p1 = __builtin_amdgcn_exp2f(lb[mt][j + 1] + cum[mt][j + 1] + carry);
.LBB0_335:
	s_or_b64 exec, exec, s[8:9]
	s_nop 1
	v_cvt_pk_bf16_f32 v44, v2, v3
	v_lshlrev_b32_e32 v46, 16, v44
	v_and_b32_e32 v47, 0xffff0000, v44
	v_pk_add_f32 v[46:47], v[2:3], v[46:47] neg_lo:[0,1] neg_hi:[0,1]
	v_cvt_pk_bf16_f32 v45, v116, v117
	v_cvt_pk_bf16_f32 v48, v46, v47
	v_lshlrev_b32_e32 v3, 16, v45
	v_and_b32_e32 v46, 0xffff0000, v45
	v_sub_f32_e32 v3, v116, v3
	v_sub_f32_e32 v46, v117, v46
	v_cvt_pk_bf16_f32 v49, v3, v46
	v_cvt_pk_bf16_f32 v46, v118, v119
	v_lshlrev_b32_e32 v3, 16, v46
	v_and_b32_e32 v47, 0xffff0000, v46
	v_sub_f32_e32 v3, v118, v3
	v_sub_f32_e32 v47, v119, v47
	v_cvt_pk_bf16_f32 v50, v3, v47
	v_cvt_pk_bf16_f32 v47, v120, v121
	v_lshlrev_b32_e32 v3, 16, v47
	v_and_b32_e32 v51, 0xffff0000, v47
	v_sub_f32_e32 v3, v120, v3
	v_sub_f32_e32 v51, v121, v51
	v_cvt_pk_bf16_f32 v52, v123, v124
	v_cvt_pk_bf16_f32 v51, v3, v51
	v_lshlrev_b32_e32 v3, 16, v52
	v_and_b32_e32 v53, 0xffff0000, v52
	v_sub_f32_e32 v3, v123, v3
	v_sub_f32_e32 v53, v124, v53
	v_cvt_pk_bf16_f32 v56, v3, v53
	v_cvt_pk_bf16_f32 v53, v125, v126
	v_lshlrev_b32_e32 v3, 16, v53
	v_and_b32_e32 v54, 0xffff0000, v53
	v_sub_f32_e32 v3, v125, v3
	v_sub_f32_e32 v54, v126, v54
	v_cvt_pk_bf16_f32 v57, v3, v54
	v_cvt_pk_bf16_f32 v54, v127, v128
	v_mfma_f32_16x16x32_bf16 v[116:119], v[8:11], v[44:47], 0
	v_lshlrev_b32_e32 v3, 16, v54
	s_mov_b32 s18, s16
	s_mov_b32 s19, s16
	v_sub_f32_e32 v3, v127, v3
	s_mov_b32 s17, s16
	v_mov_b64_e32 v[126:127], s[18:19]
	v_mov_b64_e32 v[124:125], s[16:17]
	v_mfma_f32_16x16x32_bf16 v[116:119], v[8:11], v[48:51], v[116:119]
	v_and_b32_e32 v55, 0xffff0000, v54
	v_sub_f32_e32 v55, v128, v55
	v_cvt_pk_bf16_f32 v58, v3, v55
	v_mfma_f32_16x16x32_bf16 v[44:47], v[4:7], v[44:47], 0
	v_cvt_pk_bf16_f32 v55, v130, v129
	v_lshlrev_b32_e32 v3, 16, v55
	v_and_b32_e32 v59, 0xffff0000, v55
	v_mfma_f32_16x16x32_bf16 v[116:119], v[124:127], v[52:55], v[116:119]
	v_sub_f32_e32 v3, v130, v3
	v_sub_f32_e32 v59, v129, v59
	v_cvt_pk_bf16_f32 v59, v3, v59
	v_mfma_f32_16x16x32_bf16 v[44:47], v[4:7], v[48:51], v[44:47]
	s_nop 0
	v_mfma_f32_16x16x32_bf16 v[116:119], v[124:127], v[56:59], v[116:119]
	v_mfma_f32_16x16x32_bf16 v[44:47], v[124:127], v[52:55], v[44:47]
	v_mfma_f32_16x16x32_bf16 v[48:51], v[8:11], v[52:55], 0
	s_nop 5
	v_add_f32_e32 v3, v78, v116
	v_add_f32_e32 v3, v0, v3
	v_exp_f32_e32 v3, v3
	v_mfma_f32_16x16x32_bf16 v[52:55], v[4:7], v[52:55], 0
	v_add_f32_e32 v2, v2, v116
	ds_bpermute_b32 v2, v112, v2
	v_mfma_f32_16x16x32_bf16 v[44:47], v[124:127], v[56:59], v[44:47]
	v_mfma_f32_16x16x32_bf16 v[48:51], v[8:11], v[56:59], v[48:51]
	v_mfma_f32_16x16x32_bf16 v[52:55], v[4:7], v[56:59], v[52:55]
	v_add_f32_e32 v56, v79, v117
	v_add_f32_e32 v56, v0, v56
	v_exp_f32_e32 v56, v56
	s_andn2_b64 s[8:9], exec, vcc
	s_cbranch_scc0 .Lsba_um
; __device__ __forceinline__ void phase_sba_attn(const Params& p, u16* sm) {
;     ...
;       bf16x8 pf[2];
; #pragma unroll
;       for (int k2 = 0; k2 < 2; ++k2) {
;         uint32_t pw[4];
; #pragma unroll
;         for (int e2 = 0; e2 < 4; ++e2) {
;           const int mt = 2 * k2 + (e2 >> 1), j = (e2 & 1) * 2;
;           float p0 = __builtin_amdgcn_exp2f(lb[mt][j] + cum[mt][j] + carry);
;           float p1 = __builtin_amdgcn_exp2f(lb[mt][j + 1] + cum[mt][j + 1] + carry);
;           if (tile_masked) {
;             p0 = ((vmask >> (mt * 4 + j)) & 1u) ? p0 : 0.f;
;             p1 = ((vmask >> (mt * 4 + j + 1)) & 1u) ? p1 : 0.f;
;           }
;           pw[e2] = pack2(p0, p1);
;         }
;         pf[k2] = mk_frag(pw[0], pw[1], pw[2], pw[3]);
;       }
; #pragma unroll
;       for (int k2 = 0; k2 < 2; ++k2)
; #pragma unroll
;         for (int dm = 0; dm < 4; ++dm) {
;           bf16x8 vf = *(const bf16x8*)(sV + (dm * 16 + fr) * LDSP + k2 * 32 + fq * 8);
;           o[dm] = mfma16(vf, pf[k2], o[dm]);
;         }
;       carry += tot;
	v_and_b32_e32 v57, 1, v122
	v_cmp_eq_u32_e64 s[8:9], 1, v57
	v_and_b32_e32 v57, 2, v122
	v_cmp_ne_u32_e64 s[10:11], 0, v57
	s_or_b64 s[8:9], vcc, s[8:9]
	v_cndmask_b32_e64 v3, 0, v3, s[8:9]
	s_or_b64 s[8:9], vcc, s[10:11]
	v_cndmask_b32_e64 v56, 0, v56, s[8:9]
	v_cvt_pk_bf16_f32 v56, v3, v56
	v_add_f32_e32 v3, v80, v118
	v_add_f32_e32 v3, v0, v3
	v_add_f32_e32 v57, v81, v119
	v_exp_f32_e32 v3, v3
	v_add_f32_e32 v57, v0, v57
	v_exp_f32_e32 v57, v57
	v_and_b32_e32 v58, 4, v122
	v_cmp_ne_u32_e64 s[8:9], 0, v58
	v_and_b32_e32 v58, 8, v122
	v_cmp_ne_u32_e64 s[10:11], 0, v58
	s_or_b64 s[8:9], vcc, s[8:9]
	v_cndmask_b32_e64 v3, 0, v3, s[8:9]
	s_or_b64 s[8:9], vcc, s[10:11]
	v_cndmask_b32_e64 v57, 0, v57, s[8:9]
	v_cvt_pk_bf16_f32 v57, v3, v57
	v_add_f32_e32 v3, v82, v44
	v_add_f32_e32 v3, v0, v3
	v_add_f32_e32 v44, v83, v45
	v_exp_f32_e32 v3, v3
	v_add_f32_e32 v44, v0, v44
	v_exp_f32_e32 v44, v44
	v_and_b32_e32 v45, 16, v122
	v_cmp_ne_u32_e64 s[8:9], 0, v45
	v_and_b32_e32 v45, 32, v122
	v_cmp_ne_u32_e64 s[10:11], 0, v45
	s_or_b64 s[8:9], vcc, s[8:9]
	v_cndmask_b32_e64 v3, 0, v3, s[8:9]
	s_or_b64 s[8:9], vcc, s[10:11]
	v_cndmask_b32_e64 v44, 0, v44, s[8:9]
	v_cvt_pk_bf16_f32 v58, v3, v44
	v_add_f32_e32 v3, v84, v46
	v_add_f32_e32 v3, v0, v3
	v_add_f32_e32 v44, v85, v47
	v_exp_f32_e32 v3, v3
	v_add_f32_e32 v44, v0, v44
	v_exp_f32_e32 v44, v44
	v_and_b32_e32 v45, 64, v122
	v_cmp_ne_u32_e64 s[8:9], 0, v45
	v_and_b32_e32 v45, 0x80, v122
	v_cmp_ne_u32_e64 s[10:11], 0, v45
	s_or_b64 s[8:9], vcc, s[8:9]
	v_cndmask_b32_e64 v3, 0, v3, s[8:9]
	s_or_b64 s[8:9], vcc, s[10:11]
	v_cndmask_b32_e64 v44, 0, v44, s[8:9]
	v_cvt_pk_bf16_f32 v59, v3, v44
	v_add_f32_e32 v3, v86, v48
	v_add_f32_e32 v3, v0, v3
	v_add_f32_e32 v44, v87, v49
	v_exp_f32_e32 v3, v3
	v_add_f32_e32 v44, v0, v44
	v_exp_f32_e32 v44, v44
	v_and_b32_e32 v45, 0x100, v122
	v_cmp_ne_u32_e64 s[8:9], 0, v45
	v_and_b32_e32 v45, 0x200, v122
	v_cmp_ne_u32_e64 s[10:11], 0, v45
	s_or_b64 s[8:9], vcc, s[8:9]
	v_cndmask_b32_e64 v3, 0, v3, s[8:9]
	s_or_b64 s[8:9], vcc, s[10:11]
	v_cndmask_b32_e64 v44, 0, v44, s[8:9]
	v_cvt_pk_bf16_f32 v44, v3, v44
	v_add_f32_e32 v3, v88, v50
	v_add_f32_e32 v3, v0, v3
	v_add_f32_e32 v45, v89, v51
	v_exp_f32_e32 v3, v3
	v_add_f32_e32 v45, v0, v45
	v_exp_f32_e32 v45, v45
	v_and_b32_e32 v46, 0x400, v122
	v_cmp_ne_u32_e64 s[8:9], 0, v46
	v_and_b32_e32 v46, 0x800, v122
	v_cmp_ne_u32_e64 s[10:11], 0, v46
	s_or_b64 s[8:9], vcc, s[8:9]
	v_cndmask_b32_e64 v3, 0, v3, s[8:9]
	s_or_b64 s[8:9], vcc, s[10:11]
	v_cndmask_b32_e64 v45, 0, v45, s[8:9]
	v_cvt_pk_bf16_f32 v45, v3, v45
	v_add_f32_e32 v3, v90, v52
	v_add_f32_e32 v3, v0, v3
	v_add_f32_e32 v46, v91, v53
	v_exp_f32_e32 v3, v3
	v_add_f32_e32 v46, v0, v46
	v_exp_f32_e32 v46, v46
	v_and_b32_e32 v47, 0x1000, v122
	v_cmp_ne_u32_e64 s[8:9], 0, v47
	v_and_b32_e32 v47, 0x2000, v122
	v_cmp_ne_u32_e64 s[10:11], 0, v47
	s_or_b64 s[8:9], vcc, s[8:9]
	v_cndmask_b32_e64 v3, 0, v3, s[8:9]
	s_or_b64 s[8:9], vcc, s[10:11]
	v_cndmask_b32_e64 v46, 0, v46, s[8:9]
	v_cvt_pk_bf16_f32 v46, v3, v46
	v_add_f32_e32 v3, v92, v54
	ds_read_b128 v[48:51], v115 offset:9216
	v_add_f32_e32 v47, v93, v55
	ds_read_b128 v[52:55], v115 offset:11520
	ds_read_b128 v[78:81], v115 offset:13824
	ds_read_b128 v[82:85], v115 offset:9280
	v_and_b32_e32 v86, 0x4000, v122
	s_waitcnt lgkmcnt(2)
	v_mfma_f32_16x16x32_bf16 v[36:39], v[52:55], v[56:59], v[36:39]
	v_and_b32_e32 v52, 0x8000, v122
	v_cmp_ne_u32_e64 s[8:9], 0, v86
	v_cmp_ne_u32_e64 s[10:11], 0, v52
	v_mfma_f32_16x16x32_bf16 v[40:43], v[48:51], v[56:59], v[40:43]
	ds_read_b128 v[48:51], v115 offset:16128
	ds_read_b128 v[86:89], v115 offset:11584
	ds_read_b128 v[52:55], v115 offset:13888
	v_add_f32_e32 v3, v0, v3
	s_waitcnt lgkmcnt(4)
	v_mfma_f32_16x16x32_bf16 v[24:27], v[78:81], v[56:59], v[24:27]
	ds_read_b128 v[78:81], v115 offset:16192
	v_add_f32_e32 v47, v0, v47
	v_exp_f32_e32 v3, v3
	v_exp_f32_e32 v47, v47
	s_waitcnt lgkmcnt(3)
	v_mfma_f32_16x16x32_bf16 v[20:23], v[48:51], v[56:59], v[20:23]
	s_or_b64 s[8:9], vcc, s[8:9]
	s_or_b64 vcc, vcc, s[10:11]
	v_cndmask_b32_e64 v3, 0, v3, s[8:9]
	v_cndmask_b32_e32 v47, 0, v47, vcc
	v_cvt_pk_bf16_f32 v47, v3, v47
	v_add_f32_e32 v0, v0, v2
	s_nop 0
	v_mfma_f32_16x16x32_bf16 v[40:43], v[82:85], v[44:47], v[40:43]
	s_waitcnt lgkmcnt(2)
	v_mfma_f32_16x16x32_bf16 v[36:39], v[86:89], v[44:47], v[36:39]
	s_waitcnt lgkmcnt(1)
	v_mfma_f32_16x16x32_bf16 v[24:27], v[52:55], v[44:47], v[24:27]
	s_waitcnt lgkmcnt(0)
	v_mfma_f32_16x16x32_bf16 v[20:23], v[78:81], v[44:47], v[20:23]
	s_branch .LBB0_336
	s_nop 0
	s_nop 0
	s_nop 0
	s_nop 0
.Lsba_um:
	v_cvt_pk_bf16_f32 v56, v3, v56
	v_add_f32_e32 v3, v80, v118
	v_add_f32_e32 v3, v0, v3
	v_add_f32_e32 v57, v81, v119
	v_exp_f32_e32 v3, v3
	v_add_f32_e32 v57, v0, v57
	v_exp_f32_e32 v57, v57
	s_nop 0
	v_cvt_pk_bf16_f32 v57, v3, v57
	v_add_f32_e32 v3, v82, v44
	v_add_f32_e32 v3, v0, v3
	v_add_f32_e32 v44, v83, v45
	v_exp_f32_e32 v3, v3
	v_add_f32_e32 v44, v0, v44
	v_exp_f32_e32 v44, v44
	s_nop 0
	v_cvt_pk_bf16_f32 v58, v3, v44
	v_add_f32_e32 v3, v84, v46
	v_add_f32_e32 v3, v0, v3
	v_add_f32_e32 v44, v85, v47
	v_exp_f32_e32 v3, v3
	v_add_f32_e32 v44, v0, v44
	v_exp_f32_e32 v44, v44
	s_nop 0
	v_cvt_pk_bf16_f32 v59, v3, v44
	v_add_f32_e32 v3, v86, v48
	v_add_f32_e32 v3, v0, v3
	v_add_f32_e32 v44, v87, v49
	v_exp_f32_e32 v3, v3
	v_add_f32_e32 v44, v0, v44
	v_exp_f32_e32 v44, v44
	s_nop 0
	v_cvt_pk_bf16_f32 v44, v3, v44
	v_add_f32_e32 v3, v88, v50
	v_add_f32_e32 v3, v0, v3
	v_add_f32_e32 v45, v89, v51
	v_exp_f32_e32 v3, v3
	v_add_f32_e32 v45, v0, v45
	v_exp_f32_e32 v45, v45
	s_nop 0
	v_cvt_pk_bf16_f32 v45, v3, v45
	v_add_f32_e32 v3, v90, v52
	v_add_f32_e32 v3, v0, v3
	v_add_f32_e32 v46, v91, v53
	v_exp_f32_e32 v3, v3
	v_add_f32_e32 v46, v0, v46
	v_exp_f32_e32 v46, v46
	s_nop 0
	v_cvt_pk_bf16_f32 v46, v3, v46
	v_add_f32_e32 v3, v92, v54
	ds_read_b128 v[48:51], v115 offset:9216
	v_add_f32_e32 v47, v93, v55
	ds_read_b128 v[52:55], v115 offset:11520
	ds_read_b128 v[78:81], v115 offset:13824
	ds_read_b128 v[82:85], v115 offset:9280
	s_waitcnt lgkmcnt(2)
	v_mfma_f32_16x16x32_bf16 v[36:39], v[52:55], v[56:59], v[36:39]
	v_mfma_f32_16x16x32_bf16 v[40:43], v[48:51], v[56:59], v[40:43]
	ds_read_b128 v[48:51], v115 offset:16128
	ds_read_b128 v[86:89], v115 offset:11584
	ds_read_b128 v[52:55], v115 offset:13888
	v_add_f32_e32 v3, v0, v3
	s_waitcnt lgkmcnt(4)
	v_mfma_f32_16x16x32_bf16 v[24:27], v[78:81], v[56:59], v[24:27]
	ds_read_b128 v[78:81], v115 offset:16192
	v_add_f32_e32 v47, v0, v47
	v_exp_f32_e32 v3, v3
	v_exp_f32_e32 v47, v47
	s_waitcnt lgkmcnt(3)
	v_mfma_f32_16x16x32_bf16 v[20:23], v[48:51], v[56:59], v[20:23]
	v_cvt_pk_bf16_f32 v47, v3, v47
	v_add_f32_e32 v0, v0, v2
	s_nop 0
	v_mfma_f32_16x16x32_bf16 v[40:43], v[82:85], v[44:47], v[40:43]
	s_waitcnt lgkmcnt(2)
	v_mfma_f32_16x16x32_bf16 v[36:39], v[86:89], v[44:47], v[36:39]
	s_waitcnt lgkmcnt(1)
	v_mfma_f32_16x16x32_bf16 v[24:27], v[52:55], v[44:47], v[24:27]
	s_waitcnt lgkmcnt(0)
	v_mfma_f32_16x16x32_bf16 v[20:23], v[78:81], v[44:47], v[20:23]

; #define LAS __attribute__((address_space(3)))
; __device__ __forceinline__ unsigned xb_add(unsigned* p, unsigned v) { return __hip_atomic_fetch_add(p, v, __ATOMIC_RELAXED, __HIP_MEMORY_SCOPE_AGENT); }
; __device__ __forceinline__ void grid_barrier(unsigned* bar, volatile LAS unsigned* st, unsigned k) {
;   asm volatile("s_waitcnt vmcnt(0)" ::: "memory");
;   __syncthreads();
;   if (threadIdx.x == 0) {
;     __builtin_amdgcn_s_waitcnt(0);
;     const unsigned nloc = st[0], nx = st[1], x = st[2];
;     const unsigned old = xb_add(&bar[XB_XSUB(x)], 1u);
;     if (old + 1u == (k + 1u) * nloc) {
;       __builtin_amdgcn_fence(__ATOMIC_RELEASE, "agent");
.LBB0_342:
	s_setprio 0
	s_cmp_lt_i32 s75, 3
	s_cbranch_scc1 .LBB0_386
	s_waitcnt vmcnt(0)
	s_add_i32 s0, s33, 1
	s_waitcnt vmcnt(0) lgkmcnt(0)
	s_barrier
	s_mov_b64 s[4:5], exec
	v_readlane_b32 s6, v253, 0
	v_readlane_b32 s7, v253, 1
	s_and_b64 s[6:7], s[4:5], s[6:7]
	s_mov_b64 exec, s[6:7]
	s_cbranch_execz .LBB0_385
	v_mov_b32_e32 v0, 0x20100
	s_waitcnt vmcnt(0) expcnt(0) lgkmcnt(0)
	ds_read_b32 v1, v0
	v_mov_b32_e32 v0, 0x20104
	v_mov_b32_e32 v2, 0x20108
	ds_read_b32 v0, v0
	ds_read_b32 v2, v2
	s_mov_b64 s[6:7], exec
	s_add_u32 s1, s72, 0x19008400
	s_addc_u32 s3, s73, 0
	s_mov_b32 s11, 0
	s_waitcnt lgkmcnt(0)
	v_readfirstlane_b32 s8, v2
	v_mbcnt_lo_u32_b32 v2, s6, 0
	v_mbcnt_hi_u32_b32 v2, s7, v2
	s_lshl_b32 s18, s8, 6
	v_cmp_eq_u32_e32 vcc, 0, v2
	s_and_saveexec_b64 s[8:9], vcc
	s_cbranch_execz .LBB0_346
	s_add_i32 s10, s18, 0x500
	s_lshl_b64 s[10:11], s[10:11], 2
	s_add_u32 s10, s1, s10
	s_addc_u32 s11, s3, s11
	s_bcnt1_i32_b64 s6, s[6:7]
	v_mov_b32_e32 v3, 0
	v_mov_b32_e32 v4, s6
	global_atomic_add v3, v3, v4, s[10:11] sc0
